# SwiGLU epilogue math re-emitted two row groups at a time, stage by stage (dependent results 8-16 instructions apart)
# baseline (speedup 1.0000x reference)
.LBB0_127:
	s_waitcnt lgkmcnt(0)
	s_mov_b32 s98, 0x16000
	s_mov_b32 s99, 0
	s_mov_b32 s100, 0x6e000
	s_mov_b32 s101, 0
	v_mov_b64_e32 v[188:189], s[64:65]
	v_lshl_or_b32 v190, s54, 7, v177
	v_mad_u64_u32 v[186:187], s[52:53], v164, s27, v[188:189]
	v_ashrrev_i32_e32 v191, 31, v190
	v_lshlrev_b64 v[190:191], 1, v[190:191]
	v_mul_f32_e32 v130, 0xbfb8aa3b, v170
	v_mul_f32_e32 v131, v170, v170
	v_mul_f32_e32 v168, 0xbfb8aa3b, v171
	v_mul_f32_e32 v169, v171, v171
	v_lshl_add_u64 v[186:187], v[186:187], 0, v[190:191]
	v_pk_mul_f32 v[120:121], v[124:125], v[120:121]
	v_pk_mul_f32 v[104:105], v[108:109], v[104:105]
	v_pk_mul_f32 v[122:123], v[126:127], v[122:123]
	v_pk_mul_f32 v[106:107], v[110:111], v[106:107]
	v_pk_mul_f32 v[112:113], v[116:117], v[112:113]
	v_pk_mul_f32 v[96:97], v[100:101], v[96:97]
	v_pk_mul_f32 v[114:115], v[118:119], v[114:115]
	v_pk_mul_f32 v[98:99], v[102:103], v[98:99]
	v_rcp_f32_e32 v182, v131
	v_rcp_f32_e32 v184, v169
	v_pk_mul_f32 v[124:125], v[124:125], v[130:131] op_sel_hi:[1,0]
	v_pk_mul_f32 v[108:109], v[108:109], v[168:169] op_sel_hi:[1,0]
	v_pk_mul_f32 v[126:127], v[126:127], v[130:131] op_sel_hi:[1,0]
	v_pk_mul_f32 v[110:111], v[110:111], v[168:169] op_sel_hi:[1,0]
	v_pk_mul_f32 v[116:117], v[116:117], v[130:131] op_sel_hi:[1,0]
	v_pk_mul_f32 v[100:101], v[100:101], v[168:169] op_sel_hi:[1,0]
	v_pk_mul_f32 v[118:119], v[118:119], v[130:131] op_sel_hi:[1,0]
	v_pk_mul_f32 v[102:103], v[102:103], v[168:169] op_sel_hi:[1,0]
	v_exp_f32_e32 v124, v124
	v_exp_f32_e32 v125, v125
	v_exp_f32_e32 v108, v108
	v_exp_f32_e32 v109, v109
	v_exp_f32_e32 v126, v126
	v_exp_f32_e32 v127, v127
	v_exp_f32_e32 v110, v110
	v_exp_f32_e32 v111, v111
	v_exp_f32_e32 v116, v116
	v_exp_f32_e32 v117, v117
	v_exp_f32_e32 v100, v100
	v_exp_f32_e32 v101, v101
	v_exp_f32_e32 v118, v118
	v_exp_f32_e32 v119, v119
	v_exp_f32_e32 v102, v102
	v_exp_f32_e32 v103, v103
	v_pk_fma_f32 v[124:125], v[124:125], v[182:183], v[182:183] op_sel_hi:[1,0,0]
	v_pk_fma_f32 v[108:109], v[108:109], v[184:185], v[184:185] op_sel_hi:[1,0,0]
	v_pk_fma_f32 v[126:127], v[126:127], v[182:183], v[182:183] op_sel_hi:[1,0,0]
	v_pk_fma_f32 v[110:111], v[110:111], v[184:185], v[184:185] op_sel_hi:[1,0,0]
	v_pk_fma_f32 v[116:117], v[116:117], v[182:183], v[182:183] op_sel_hi:[1,0,0]
	v_pk_fma_f32 v[100:101], v[100:101], v[184:185], v[184:185] op_sel_hi:[1,0,0]
	v_pk_fma_f32 v[118:119], v[118:119], v[182:183], v[182:183] op_sel_hi:[1,0,0]
	v_pk_fma_f32 v[102:103], v[102:103], v[184:185], v[184:185] op_sel_hi:[1,0,0]
	v_rcp_f32_e32 v124, v124
	v_rcp_f32_e32 v125, v125
	v_rcp_f32_e32 v108, v108
	v_rcp_f32_e32 v109, v109
	v_rcp_f32_e32 v126, v126
	v_rcp_f32_e32 v127, v127
	v_rcp_f32_e32 v110, v110
	v_rcp_f32_e32 v111, v111
	v_rcp_f32_e32 v116, v116
	v_rcp_f32_e32 v117, v117
	v_rcp_f32_e32 v100, v100
	v_rcp_f32_e32 v101, v101
	v_rcp_f32_e32 v118, v118
	v_rcp_f32_e32 v119, v119
	v_rcp_f32_e32 v102, v102
	v_rcp_f32_e32 v103, v103
	v_pk_mul_f32 v[120:121], v[120:121], v[124:125]
	v_pk_mul_f32 v[104:105], v[104:105], v[108:109]
	v_pk_mul_f32 v[122:123], v[122:123], v[126:127]
	v_pk_mul_f32 v[106:107], v[106:107], v[110:111]
	v_pk_mul_f32 v[112:113], v[112:113], v[116:117]
	v_pk_mul_f32 v[96:97], v[96:97], v[100:101]
	v_pk_mul_f32 v[114:115], v[114:115], v[118:119]
	v_pk_mul_f32 v[98:99], v[98:99], v[102:103]
	v_cvt_pk_bf16_f32 v116, v120, v121
	v_cvt_pk_bf16_f32 v117, v122, v123
	v_cvt_pk_bf16_f32 v118, v112, v113
	v_cvt_pk_bf16_f32 v119, v114, v115
	v_cvt_pk_bf16_f32 v100, v104, v105
	v_cvt_pk_bf16_f32 v101, v106, v107
	v_cvt_pk_bf16_f32 v102, v96, v97
	v_cvt_pk_bf16_f32 v103, v98, v99
	global_store_dwordx4 v[186:187], v[116:119], off
	v_lshl_add_u64 v[186:187], v[186:187], 0, s[98:99]
	s_nop 0
	global_store_dwordx4 v[186:187], v[100:103], off
	v_lshl_add_u64 v[186:187], v[186:187], 0, s[98:99]
	v_mul_f32_e32 v130, 0xbfb8aa3b, v166
	v_mul_f32_e32 v131, v166, v166
	v_mul_f32_e32 v168, 0xbfb8aa3b, v167
	v_mul_f32_e32 v169, v167, v167
	v_pk_mul_f32 v[88:89], v[92:93], v[88:89]
	v_pk_mul_f32 v[72:73], v[76:77], v[72:73]
	v_pk_mul_f32 v[90:91], v[94:95], v[90:91]
	v_pk_mul_f32 v[74:75], v[78:79], v[74:75]
	v_pk_mul_f32 v[80:81], v[84:85], v[80:81]
	v_pk_mul_f32 v[64:65], v[68:69], v[64:65]
	v_pk_mul_f32 v[82:83], v[86:87], v[82:83]
	v_pk_mul_f32 v[66:67], v[70:71], v[66:67]
	v_rcp_f32_e32 v182, v131
	v_rcp_f32_e32 v184, v169
	v_pk_mul_f32 v[92:93], v[92:93], v[130:131] op_sel_hi:[1,0]
	v_pk_mul_f32 v[76:77], v[76:77], v[168:169] op_sel_hi:[1,0]
	v_pk_mul_f32 v[94:95], v[94:95], v[130:131] op_sel_hi:[1,0]
	v_pk_mul_f32 v[78:79], v[78:79], v[168:169] op_sel_hi:[1,0]
	v_pk_mul_f32 v[84:85], v[84:85], v[130:131] op_sel_hi:[1,0]
	v_pk_mul_f32 v[68:69], v[68:69], v[168:169] op_sel_hi:[1,0]
	v_pk_mul_f32 v[86:87], v[86:87], v[130:131] op_sel_hi:[1,0]
	v_pk_mul_f32 v[70:71], v[70:71], v[168:169] op_sel_hi:[1,0]
	v_exp_f32_e32 v92, v92
	v_exp_f32_e32 v93, v93
	v_exp_f32_e32 v76, v76
	v_exp_f32_e32 v77, v77
	v_exp_f32_e32 v94, v94
	v_exp_f32_e32 v95, v95
	v_exp_f32_e32 v78, v78
	v_exp_f32_e32 v79, v79
	v_exp_f32_e32 v84, v84
	v_exp_f32_e32 v85, v85
	v_exp_f32_e32 v68, v68
	v_exp_f32_e32 v69, v69
	v_exp_f32_e32 v86, v86
	v_exp_f32_e32 v87, v87
	v_exp_f32_e32 v70, v70
	v_exp_f32_e32 v71, v71
	v_pk_fma_f32 v[92:93], v[92:93], v[182:183], v[182:183] op_sel_hi:[1,0,0]
	v_pk_fma_f32 v[76:77], v[76:77], v[184:185], v[184:185] op_sel_hi:[1,0,0]
	v_pk_fma_f32 v[94:95], v[94:95], v[182:183], v[182:183] op_sel_hi:[1,0,0]
	v_pk_fma_f32 v[78:79], v[78:79], v[184:185], v[184:185] op_sel_hi:[1,0,0]
	v_pk_fma_f32 v[84:85], v[84:85], v[182:183], v[182:183] op_sel_hi:[1,0,0]
	v_pk_fma_f32 v[68:69], v[68:69], v[184:185], v[184:185] op_sel_hi:[1,0,0]
	v_pk_fma_f32 v[86:87], v[86:87], v[182:183], v[182:183] op_sel_hi:[1,0,0]
	v_pk_fma_f32 v[70:71], v[70:71], v[184:185], v[184:185] op_sel_hi:[1,0,0]
	v_rcp_f32_e32 v92, v92
	v_rcp_f32_e32 v93, v93
	v_rcp_f32_e32 v76, v76
	v_rcp_f32_e32 v77, v77
	v_rcp_f32_e32 v94, v94
	v_rcp_f32_e32 v95, v95
	v_rcp_f32_e32 v78, v78
	v_rcp_f32_e32 v79, v79
	v_rcp_f32_e32 v84, v84
	v_rcp_f32_e32 v85, v85
	v_rcp_f32_e32 v68, v68
	v_rcp_f32_e32 v69, v69
	v_rcp_f32_e32 v86, v86
	v_rcp_f32_e32 v87, v87
	v_rcp_f32_e32 v70, v70
	v_rcp_f32_e32 v71, v71
	v_pk_mul_f32 v[88:89], v[88:89], v[92:93]
	v_pk_mul_f32 v[72:73], v[72:73], v[76:77]
	v_pk_mul_f32 v[90:91], v[90:91], v[94:95]
	v_pk_mul_f32 v[74:75], v[74:75], v[78:79]
	v_pk_mul_f32 v[80:81], v[80:81], v[84:85]
	v_pk_mul_f32 v[64:65], v[64:65], v[68:69]
	v_pk_mul_f32 v[82:83], v[82:83], v[86:87]
	v_pk_mul_f32 v[66:67], v[66:67], v[70:71]
	v_cvt_pk_bf16_f32 v84, v88, v89
	v_cvt_pk_bf16_f32 v85, v90, v91
	v_cvt_pk_bf16_f32 v86, v80, v81
	v_cvt_pk_bf16_f32 v87, v82, v83
	v_cvt_pk_bf16_f32 v68, v72, v73
	v_cvt_pk_bf16_f32 v69, v74, v75
	v_cvt_pk_bf16_f32 v70, v64, v65
	v_cvt_pk_bf16_f32 v71, v66, v67
	global_store_dwordx4 v[186:187], v[84:87], off
	v_lshl_add_u64 v[186:187], v[186:187], 0, s[98:99]
	s_nop 0
	global_store_dwordx4 v[186:187], v[68:71], off
	v_lshl_add_u64 v[186:187], v[186:187], 0, s[100:101]
	v_mul_f32_e32 v130, 0xbfb8aa3b, v162
	v_mul_f32_e32 v131, v162, v162
	v_mul_f32_e32 v168, 0xbfb8aa3b, v163
	v_mul_f32_e32 v169, v163, v163
	v_pk_mul_f32 v[56:57], v[60:61], v[56:57]
	v_pk_mul_f32 v[40:41], v[44:45], v[40:41]
	v_pk_mul_f32 v[58:59], v[62:63], v[58:59]
	v_pk_mul_f32 v[42:43], v[46:47], v[42:43]
	v_pk_mul_f32 v[48:49], v[52:53], v[48:49]
	v_pk_mul_f32 v[32:33], v[36:37], v[32:33]
	v_pk_mul_f32 v[50:51], v[54:55], v[50:51]
	v_pk_mul_f32 v[34:35], v[38:39], v[34:35]
	v_rcp_f32_e32 v182, v131
	v_rcp_f32_e32 v184, v169
	v_pk_mul_f32 v[60:61], v[60:61], v[130:131] op_sel_hi:[1,0]
	v_pk_mul_f32 v[44:45], v[44:45], v[168:169] op_sel_hi:[1,0]
	v_pk_mul_f32 v[62:63], v[62:63], v[130:131] op_sel_hi:[1,0]
	v_pk_mul_f32 v[46:47], v[46:47], v[168:169] op_sel_hi:[1,0]
	v_pk_mul_f32 v[52:53], v[52:53], v[130:131] op_sel_hi:[1,0]
	v_pk_mul_f32 v[36:37], v[36:37], v[168:169] op_sel_hi:[1,0]
	v_pk_mul_f32 v[54:55], v[54:55], v[130:131] op_sel_hi:[1,0]
	v_pk_mul_f32 v[38:39], v[38:39], v[168:169] op_sel_hi:[1,0]
	v_exp_f32_e32 v60, v60
	v_exp_f32_e32 v61, v61
	v_exp_f32_e32 v44, v44
	v_exp_f32_e32 v45, v45
	v_exp_f32_e32 v62, v62
	v_exp_f32_e32 v63, v63
	v_exp_f32_e32 v46, v46
	v_exp_f32_e32 v47, v47
	v_exp_f32_e32 v52, v52
	v_exp_f32_e32 v53, v53
	v_exp_f32_e32 v36, v36
	v_exp_f32_e32 v37, v37
	v_exp_f32_e32 v54, v54
	v_exp_f32_e32 v55, v55
	v_exp_f32_e32 v38, v38
	v_exp_f32_e32 v39, v39
	v_pk_fma_f32 v[60:61], v[60:61], v[182:183], v[182:183] op_sel_hi:[1,0,0]
	v_pk_fma_f32 v[44:45], v[44:45], v[184:185], v[184:185] op_sel_hi:[1,0,0]
	v_pk_fma_f32 v[62:63], v[62:63], v[182:183], v[182:183] op_sel_hi:[1,0,0]
	v_pk_fma_f32 v[46:47], v[46:47], v[184:185], v[184:185] op_sel_hi:[1,0,0]
	v_pk_fma_f32 v[52:53], v[52:53], v[182:183], v[182:183] op_sel_hi:[1,0,0]
	v_pk_fma_f32 v[36:37], v[36:37], v[184:185], v[184:185] op_sel_hi:[1,0,0]
	v_pk_fma_f32 v[54:55], v[54:55], v[182:183], v[182:183] op_sel_hi:[1,0,0]
	v_pk_fma_f32 v[38:39], v[38:39], v[184:185], v[184:185] op_sel_hi:[1,0,0]
	v_rcp_f32_e32 v60, v60
	v_rcp_f32_e32 v61, v61
	v_rcp_f32_e32 v44, v44
	v_rcp_f32_e32 v45, v45
	v_rcp_f32_e32 v62, v62
	v_rcp_f32_e32 v63, v63
	v_rcp_f32_e32 v46, v46
	v_rcp_f32_e32 v47, v47
	v_rcp_f32_e32 v52, v52
	v_rcp_f32_e32 v53, v53
	v_rcp_f32_e32 v36, v36
	v_rcp_f32_e32 v37, v37
	v_rcp_f32_e32 v54, v54
	v_rcp_f32_e32 v55, v55
	v_rcp_f32_e32 v38, v38
	v_rcp_f32_e32 v39, v39
	v_pk_mul_f32 v[56:57], v[56:57], v[60:61]
	v_pk_mul_f32 v[40:41], v[40:41], v[44:45]
	v_pk_mul_f32 v[58:59], v[58:59], v[62:63]
	v_pk_mul_f32 v[42:43], v[42:43], v[46:47]
	v_pk_mul_f32 v[48:49], v[48:49], v[52:53]
	v_pk_mul_f32 v[32:33], v[32:33], v[36:37]
	v_pk_mul_f32 v[50:51], v[50:51], v[54:55]
	v_pk_mul_f32 v[34:35], v[34:35], v[38:39]
	v_cvt_pk_bf16_f32 v52, v56, v57
	v_cvt_pk_bf16_f32 v53, v58, v59
	v_cvt_pk_bf16_f32 v54, v48, v49
	v_cvt_pk_bf16_f32 v55, v50, v51
	v_cvt_pk_bf16_f32 v36, v40, v41
	v_cvt_pk_bf16_f32 v37, v42, v43
	v_cvt_pk_bf16_f32 v38, v32, v33
	v_cvt_pk_bf16_f32 v39, v34, v35
	global_store_dwordx4 v[186:187], v[52:55], off
	v_lshl_add_u64 v[186:187], v[186:187], 0, s[98:99]
	s_nop 0
	global_store_dwordx4 v[186:187], v[36:39], off
	v_lshl_add_u64 v[186:187], v[186:187], 0, s[98:99]
	v_mul_f32_e32 v130, 0xbfb8aa3b, v132
	v_mul_f32_e32 v131, v132, v132
	v_mul_f32_e32 v168, 0xbfb8aa3b, v133
	v_mul_f32_e32 v169, v133, v133
	v_pk_mul_f32 v[24:25], v[28:29], v[24:25]
	v_pk_mul_f32 v[8:9], v[12:13], v[8:9]
	v_pk_mul_f32 v[26:27], v[30:31], v[26:27]
	v_pk_mul_f32 v[10:11], v[14:15], v[10:11]
	v_pk_mul_f32 v[16:17], v[20:21], v[16:17]
	v_pk_mul_f32 v[0:1], v[4:5], v[0:1]
	v_pk_mul_f32 v[18:19], v[22:23], v[18:19]
	v_pk_mul_f32 v[2:3], v[6:7], v[2:3]
	v_rcp_f32_e32 v182, v131
	v_rcp_f32_e32 v184, v169
	v_pk_mul_f32 v[28:29], v[28:29], v[130:131] op_sel_hi:[1,0]
	v_pk_mul_f32 v[12:13], v[12:13], v[168:169] op_sel_hi:[1,0]
	v_pk_mul_f32 v[30:31], v[30:31], v[130:131] op_sel_hi:[1,0]
	v_pk_mul_f32 v[14:15], v[14:15], v[168:169] op_sel_hi:[1,0]
	v_pk_mul_f32 v[20:21], v[20:21], v[130:131] op_sel_hi:[1,0]
	v_pk_mul_f32 v[4:5], v[4:5], v[168:169] op_sel_hi:[1,0]
	v_pk_mul_f32 v[22:23], v[22:23], v[130:131] op_sel_hi:[1,0]
	v_pk_mul_f32 v[6:7], v[6:7], v[168:169] op_sel_hi:[1,0]
	v_exp_f32_e32 v28, v28
	v_exp_f32_e32 v29, v29
	v_exp_f32_e32 v12, v12
	v_exp_f32_e32 v13, v13
	v_exp_f32_e32 v30, v30
	v_exp_f32_e32 v31, v31
	v_exp_f32_e32 v14, v14
	v_exp_f32_e32 v15, v15
	v_exp_f32_e32 v20, v20
	v_exp_f32_e32 v21, v21
	v_exp_f32_e32 v4, v4
	v_exp_f32_e32 v5, v5
	v_exp_f32_e32 v22, v22
	v_exp_f32_e32 v23, v23
	v_exp_f32_e32 v6, v6
	v_exp_f32_e32 v7, v7
	v_pk_fma_f32 v[28:29], v[28:29], v[182:183], v[182:183] op_sel_hi:[1,0,0]
	v_pk_fma_f32 v[12:13], v[12:13], v[184:185], v[184:185] op_sel_hi:[1,0,0]
	v_pk_fma_f32 v[30:31], v[30:31], v[182:183], v[182:183] op_sel_hi:[1,0,0]
	v_pk_fma_f32 v[14:15], v[14:15], v[184:185], v[184:185] op_sel_hi:[1,0,0]
	v_pk_fma_f32 v[20:21], v[20:21], v[182:183], v[182:183] op_sel_hi:[1,0,0]
	v_pk_fma_f32 v[4:5], v[4:5], v[184:185], v[184:185] op_sel_hi:[1,0,0]
	v_pk_fma_f32 v[22:23], v[22:23], v[182:183], v[182:183] op_sel_hi:[1,0,0]
	v_pk_fma_f32 v[6:7], v[6:7], v[184:185], v[184:185] op_sel_hi:[1,0,0]
	v_rcp_f32_e32 v28, v28
	v_rcp_f32_e32 v29, v29
	v_rcp_f32_e32 v12, v12
	v_rcp_f32_e32 v13, v13
	v_rcp_f32_e32 v30, v30
	v_rcp_f32_e32 v31, v31
	v_rcp_f32_e32 v14, v14
	v_rcp_f32_e32 v15, v15
	v_rcp_f32_e32 v20, v20
	v_rcp_f32_e32 v21, v21
	v_rcp_f32_e32 v4, v4
	v_rcp_f32_e32 v5, v5
	v_rcp_f32_e32 v22, v22
	v_rcp_f32_e32 v23, v23
	v_rcp_f32_e32 v6, v6
	v_rcp_f32_e32 v7, v7
	v_pk_mul_f32 v[24:25], v[24:25], v[28:29]
	v_pk_mul_f32 v[8:9], v[8:9], v[12:13]
	v_pk_mul_f32 v[26:27], v[26:27], v[30:31]
	v_pk_mul_f32 v[10:11], v[10:11], v[14:15]
	v_pk_mul_f32 v[16:17], v[16:17], v[20:21]
	v_pk_mul_f32 v[0:1], v[0:1], v[4:5]
	v_pk_mul_f32 v[18:19], v[18:19], v[22:23]
	v_pk_mul_f32 v[2:3], v[2:3], v[6:7]
	v_cvt_pk_bf16_f32 v20, v24, v25
	v_cvt_pk_bf16_f32 v21, v26, v27
	v_cvt_pk_bf16_f32 v22, v16, v17
	v_cvt_pk_bf16_f32 v23, v18, v19
	v_cvt_pk_bf16_f32 v4, v8, v9
	v_cvt_pk_bf16_f32 v5, v10, v11
	v_cvt_pk_bf16_f32 v6, v0, v1
	v_cvt_pk_bf16_f32 v7, v2, v3
	global_store_dwordx4 v[186:187], v[20:23], off
	v_lshl_add_u64 v[186:187], v[186:187], 0, s[98:99]
	s_nop 0
	global_store_dwordx4 v[186:187], v[4:7], off
	s_andn2_b64 vcc, exec, s[6:7]
	s_mov_b64 s[6:7], -1
	s_cbranch_vccnz .LBB0_116
	s_andn2_b64 vcc, exec, s[10:11]
	s_cbranch_vccnz .LBB0_115
	s_barrier
	s_branch .LBB0_115

.LBB0_1155:
	s_waitcnt lgkmcnt(0)
	s_mov_b32 s98, 0x16000
	s_mov_b32 s99, 0
	s_mov_b32 s100, 0x6e000
	s_mov_b32 s101, 0
	v_mov_b64_e32 v[188:189], s[64:65]
	v_lshl_or_b32 v190, s56, 7, v173
	v_mad_u64_u32 v[186:187], s[54:55], v160, s27, v[188:189]
	v_ashrrev_i32_e32 v191, 31, v190
	v_lshlrev_b64 v[190:191], 1, v[190:191]
	v_mul_f32_e32 v178, 0xbfb8aa3b, v166
	v_mul_f32_e32 v179, v166, v166
	v_mul_f32_e32 v180, 0xbfb8aa3b, v167
	v_mul_f32_e32 v181, v167, v167
	v_lshl_add_u64 v[186:187], v[186:187], 0, v[190:191]
	v_pk_mul_f32 v[120:121], v[124:125], v[120:121]
	v_pk_mul_f32 v[104:105], v[108:109], v[104:105]
	v_pk_mul_f32 v[122:123], v[126:127], v[122:123]
	v_pk_mul_f32 v[106:107], v[110:111], v[106:107]
	v_pk_mul_f32 v[112:113], v[116:117], v[112:113]
	v_pk_mul_f32 v[96:97], v[100:101], v[96:97]
	v_pk_mul_f32 v[114:115], v[118:119], v[114:115]
	v_pk_mul_f32 v[98:99], v[102:103], v[98:99]
	v_rcp_f32_e32 v182, v179
	v_rcp_f32_e32 v184, v181
	v_pk_mul_f32 v[124:125], v[124:125], v[178:179] op_sel_hi:[1,0]
	v_pk_mul_f32 v[108:109], v[108:109], v[180:181] op_sel_hi:[1,0]
	v_pk_mul_f32 v[126:127], v[126:127], v[178:179] op_sel_hi:[1,0]
	v_pk_mul_f32 v[110:111], v[110:111], v[180:181] op_sel_hi:[1,0]
	v_pk_mul_f32 v[116:117], v[116:117], v[178:179] op_sel_hi:[1,0]
	v_pk_mul_f32 v[100:101], v[100:101], v[180:181] op_sel_hi:[1,0]
	v_pk_mul_f32 v[118:119], v[118:119], v[178:179] op_sel_hi:[1,0]
	v_pk_mul_f32 v[102:103], v[102:103], v[180:181] op_sel_hi:[1,0]
	v_exp_f32_e32 v124, v124
	v_exp_f32_e32 v125, v125
	v_exp_f32_e32 v108, v108
	v_exp_f32_e32 v109, v109
	v_exp_f32_e32 v126, v126
	v_exp_f32_e32 v127, v127
	v_exp_f32_e32 v110, v110
	v_exp_f32_e32 v111, v111
	v_exp_f32_e32 v116, v116
	v_exp_f32_e32 v117, v117
	v_exp_f32_e32 v100, v100
	v_exp_f32_e32 v101, v101
	v_exp_f32_e32 v118, v118
	v_exp_f32_e32 v119, v119
	v_exp_f32_e32 v102, v102
	v_exp_f32_e32 v103, v103
	v_pk_fma_f32 v[124:125], v[124:125], v[182:183], v[182:183] op_sel_hi:[1,0,0]
	v_pk_fma_f32 v[108:109], v[108:109], v[184:185], v[184:185] op_sel_hi:[1,0,0]
	v_pk_fma_f32 v[126:127], v[126:127], v[182:183], v[182:183] op_sel_hi:[1,0,0]
	v_pk_fma_f32 v[110:111], v[110:111], v[184:185], v[184:185] op_sel_hi:[1,0,0]
	v_pk_fma_f32 v[116:117], v[116:117], v[182:183], v[182:183] op_sel_hi:[1,0,0]
	v_pk_fma_f32 v[100:101], v[100:101], v[184:185], v[184:185] op_sel_hi:[1,0,0]
	v_pk_fma_f32 v[118:119], v[118:119], v[182:183], v[182:183] op_sel_hi:[1,0,0]
	v_pk_fma_f32 v[102:103], v[102:103], v[184:185], v[184:185] op_sel_hi:[1,0,0]
	v_rcp_f32_e32 v124, v124
	v_rcp_f32_e32 v125, v125
	v_rcp_f32_e32 v108, v108
	v_rcp_f32_e32 v109, v109
	v_rcp_f32_e32 v126, v126
	v_rcp_f32_e32 v127, v127
	v_rcp_f32_e32 v110, v110
	v_rcp_f32_e32 v111, v111
	v_rcp_f32_e32 v116, v116
	v_rcp_f32_e32 v117, v117
	v_rcp_f32_e32 v100, v100
	v_rcp_f32_e32 v101, v101
	v_rcp_f32_e32 v118, v118
	v_rcp_f32_e32 v119, v119
	v_rcp_f32_e32 v102, v102
	v_rcp_f32_e32 v103, v103
	v_pk_mul_f32 v[120:121], v[120:121], v[124:125]
	v_pk_mul_f32 v[104:105], v[104:105], v[108:109]
	v_pk_mul_f32 v[122:123], v[122:123], v[126:127]
	v_pk_mul_f32 v[106:107], v[106:107], v[110:111]
	v_pk_mul_f32 v[112:113], v[112:113], v[116:117]
	v_pk_mul_f32 v[96:97], v[96:97], v[100:101]
	v_pk_mul_f32 v[114:115], v[114:115], v[118:119]
	v_pk_mul_f32 v[98:99], v[98:99], v[102:103]
	v_cvt_pk_bf16_f32 v116, v120, v121
	v_cvt_pk_bf16_f32 v117, v122, v123
	v_cvt_pk_bf16_f32 v118, v112, v113
	v_cvt_pk_bf16_f32 v119, v114, v115
	v_cvt_pk_bf16_f32 v100, v104, v105
	v_cvt_pk_bf16_f32 v101, v106, v107
	v_cvt_pk_bf16_f32 v102, v96, v97
	v_cvt_pk_bf16_f32 v103, v98, v99
	global_store_dwordx4 v[186:187], v[116:119], off
	v_lshl_add_u64 v[186:187], v[186:187], 0, s[98:99]
	s_nop 0
	global_store_dwordx4 v[186:187], v[100:103], off
	v_lshl_add_u64 v[186:187], v[186:187], 0, s[98:99]
	v_mul_f32_e32 v178, 0xbfb8aa3b, v162
	v_mul_f32_e32 v179, v162, v162
	v_mul_f32_e32 v180, 0xbfb8aa3b, v163
	v_mul_f32_e32 v181, v163, v163
	v_pk_mul_f32 v[88:89], v[92:93], v[88:89]
	v_pk_mul_f32 v[72:73], v[76:77], v[72:73]
	v_pk_mul_f32 v[90:91], v[94:95], v[90:91]
	v_pk_mul_f32 v[74:75], v[78:79], v[74:75]
	v_pk_mul_f32 v[80:81], v[84:85], v[80:81]
	v_pk_mul_f32 v[64:65], v[68:69], v[64:65]
	v_pk_mul_f32 v[82:83], v[86:87], v[82:83]
	v_pk_mul_f32 v[66:67], v[70:71], v[66:67]
	v_rcp_f32_e32 v182, v179
	v_rcp_f32_e32 v184, v181
	v_pk_mul_f32 v[92:93], v[92:93], v[178:179] op_sel_hi:[1,0]
	v_pk_mul_f32 v[76:77], v[76:77], v[180:181] op_sel_hi:[1,0]
	v_pk_mul_f32 v[94:95], v[94:95], v[178:179] op_sel_hi:[1,0]
	v_pk_mul_f32 v[78:79], v[78:79], v[180:181] op_sel_hi:[1,0]
	v_pk_mul_f32 v[84:85], v[84:85], v[178:179] op_sel_hi:[1,0]
	v_pk_mul_f32 v[68:69], v[68:69], v[180:181] op_sel_hi:[1,0]
	v_pk_mul_f32 v[86:87], v[86:87], v[178:179] op_sel_hi:[1,0]
	v_pk_mul_f32 v[70:71], v[70:71], v[180:181] op_sel_hi:[1,0]
	v_exp_f32_e32 v92, v92
	v_exp_f32_e32 v93, v93
	v_exp_f32_e32 v76, v76
	v_exp_f32_e32 v77, v77
	v_exp_f32_e32 v94, v94
	v_exp_f32_e32 v95, v95
	v_exp_f32_e32 v78, v78
	v_exp_f32_e32 v79, v79
	v_exp_f32_e32 v84, v84
	v_exp_f32_e32 v85, v85
	v_exp_f32_e32 v68, v68
	v_exp_f32_e32 v69, v69
	v_exp_f32_e32 v86, v86
	v_exp_f32_e32 v87, v87
	v_exp_f32_e32 v70, v70
	v_exp_f32_e32 v71, v71
	v_pk_fma_f32 v[92:93], v[92:93], v[182:183], v[182:183] op_sel_hi:[1,0,0]
	v_pk_fma_f32 v[76:77], v[76:77], v[184:185], v[184:185] op_sel_hi:[1,0,0]
	v_pk_fma_f32 v[94:95], v[94:95], v[182:183], v[182:183] op_sel_hi:[1,0,0]
	v_pk_fma_f32 v[78:79], v[78:79], v[184:185], v[184:185] op_sel_hi:[1,0,0]
	v_pk_fma_f32 v[84:85], v[84:85], v[182:183], v[182:183] op_sel_hi:[1,0,0]
	v_pk_fma_f32 v[68:69], v[68:69], v[184:185], v[184:185] op_sel_hi:[1,0,0]
	v_pk_fma_f32 v[86:87], v[86:87], v[182:183], v[182:183] op_sel_hi:[1,0,0]
	v_pk_fma_f32 v[70:71], v[70:71], v[184:185], v[184:185] op_sel_hi:[1,0,0]
	v_rcp_f32_e32 v92, v92
	v_rcp_f32_e32 v93, v93
	v_rcp_f32_e32 v76, v76
	v_rcp_f32_e32 v77, v77
	v_rcp_f32_e32 v94, v94
	v_rcp_f32_e32 v95, v95
	v_rcp_f32_e32 v78, v78
	v_rcp_f32_e32 v79, v79
	v_rcp_f32_e32 v84, v84
	v_rcp_f32_e32 v85, v85
	v_rcp_f32_e32 v68, v68
	v_rcp_f32_e32 v69, v69
	v_rcp_f32_e32 v86, v86
	v_rcp_f32_e32 v87, v87
	v_rcp_f32_e32 v70, v70
	v_rcp_f32_e32 v71, v71
	v_pk_mul_f32 v[88:89], v[88:89], v[92:93]
	v_pk_mul_f32 v[72:73], v[72:73], v[76:77]
	v_pk_mul_f32 v[90:91], v[90:91], v[94:95]
	v_pk_mul_f32 v[74:75], v[74:75], v[78:79]
	v_pk_mul_f32 v[80:81], v[80:81], v[84:85]
	v_pk_mul_f32 v[64:65], v[64:65], v[68:69]
	v_pk_mul_f32 v[82:83], v[82:83], v[86:87]
	v_pk_mul_f32 v[66:67], v[66:67], v[70:71]
	v_cvt_pk_bf16_f32 v84, v88, v89
	v_cvt_pk_bf16_f32 v85, v90, v91
	v_cvt_pk_bf16_f32 v86, v80, v81
	v_cvt_pk_bf16_f32 v87, v82, v83
	v_cvt_pk_bf16_f32 v68, v72, v73
	v_cvt_pk_bf16_f32 v69, v74, v75
	v_cvt_pk_bf16_f32 v70, v64, v65
	v_cvt_pk_bf16_f32 v71, v66, v67
	global_store_dwordx4 v[186:187], v[84:87], off
	v_lshl_add_u64 v[186:187], v[186:187], 0, s[98:99]
	s_nop 0
	global_store_dwordx4 v[186:187], v[68:71], off
	v_lshl_add_u64 v[186:187], v[186:187], 0, s[100:101]
	v_mul_f32_e32 v178, 0xbfb8aa3b, v154
	v_mul_f32_e32 v179, v154, v154
	v_mul_f32_e32 v180, 0xbfb8aa3b, v155
	v_mul_f32_e32 v181, v155, v155
	v_pk_mul_f32 v[56:57], v[60:61], v[56:57]
	v_pk_mul_f32 v[40:41], v[44:45], v[40:41]
	v_pk_mul_f32 v[58:59], v[62:63], v[58:59]
	v_pk_mul_f32 v[42:43], v[46:47], v[42:43]
	v_pk_mul_f32 v[48:49], v[52:53], v[48:49]
	v_pk_mul_f32 v[32:33], v[36:37], v[32:33]
	v_pk_mul_f32 v[50:51], v[54:55], v[50:51]
	v_pk_mul_f32 v[34:35], v[38:39], v[34:35]
	v_rcp_f32_e32 v182, v179
	v_rcp_f32_e32 v184, v181
	v_pk_mul_f32 v[60:61], v[60:61], v[178:179] op_sel_hi:[1,0]
	v_pk_mul_f32 v[44:45], v[44:45], v[180:181] op_sel_hi:[1,0]
	v_pk_mul_f32 v[62:63], v[62:63], v[178:179] op_sel_hi:[1,0]
	v_pk_mul_f32 v[46:47], v[46:47], v[180:181] op_sel_hi:[1,0]
	v_pk_mul_f32 v[52:53], v[52:53], v[178:179] op_sel_hi:[1,0]
	v_pk_mul_f32 v[36:37], v[36:37], v[180:181] op_sel_hi:[1,0]
	v_pk_mul_f32 v[54:55], v[54:55], v[178:179] op_sel_hi:[1,0]
	v_pk_mul_f32 v[38:39], v[38:39], v[180:181] op_sel_hi:[1,0]
	v_exp_f32_e32 v60, v60
	v_exp_f32_e32 v61, v61
	v_exp_f32_e32 v44, v44
	v_exp_f32_e32 v45, v45
	v_exp_f32_e32 v62, v62
	v_exp_f32_e32 v63, v63
	v_exp_f32_e32 v46, v46
	v_exp_f32_e32 v47, v47
	v_exp_f32_e32 v52, v52
	v_exp_f32_e32 v53, v53
	v_exp_f32_e32 v36, v36
	v_exp_f32_e32 v37, v37
	v_exp_f32_e32 v54, v54
	v_exp_f32_e32 v55, v55
	v_exp_f32_e32 v38, v38
	v_exp_f32_e32 v39, v39
	v_pk_fma_f32 v[60:61], v[60:61], v[182:183], v[182:183] op_sel_hi:[1,0,0]
	v_pk_fma_f32 v[44:45], v[44:45], v[184:185], v[184:185] op_sel_hi:[1,0,0]
	v_pk_fma_f32 v[62:63], v[62:63], v[182:183], v[182:183] op_sel_hi:[1,0,0]
	v_pk_fma_f32 v[46:47], v[46:47], v[184:185], v[184:185] op_sel_hi:[1,0,0]
	v_pk_fma_f32 v[52:53], v[52:53], v[182:183], v[182:183] op_sel_hi:[1,0,0]
	v_pk_fma_f32 v[36:37], v[36:37], v[184:185], v[184:185] op_sel_hi:[1,0,0]
	v_pk_fma_f32 v[54:55], v[54:55], v[182:183], v[182:183] op_sel_hi:[1,0,0]
	v_pk_fma_f32 v[38:39], v[38:39], v[184:185], v[184:185] op_sel_hi:[1,0,0]
	v_rcp_f32_e32 v60, v60
	v_rcp_f32_e32 v61, v61
	v_rcp_f32_e32 v44, v44
	v_rcp_f32_e32 v45, v45
	v_rcp_f32_e32 v62, v62
	v_rcp_f32_e32 v63, v63
	v_rcp_f32_e32 v46, v46
	v_rcp_f32_e32 v47, v47
	v_rcp_f32_e32 v52, v52
	v_rcp_f32_e32 v53, v53
	v_rcp_f32_e32 v36, v36
	v_rcp_f32_e32 v37, v37
	v_rcp_f32_e32 v54, v54
	v_rcp_f32_e32 v55, v55
	v_rcp_f32_e32 v38, v38
	v_rcp_f32_e32 v39, v39
	v_pk_mul_f32 v[56:57], v[56:57], v[60:61]
	v_pk_mul_f32 v[40:41], v[40:41], v[44:45]
	v_pk_mul_f32 v[58:59], v[58:59], v[62:63]
	v_pk_mul_f32 v[42:43], v[42:43], v[46:47]
	v_pk_mul_f32 v[48:49], v[48:49], v[52:53]
	v_pk_mul_f32 v[32:33], v[32:33], v[36:37]
	v_pk_mul_f32 v[50:51], v[50:51], v[54:55]
	v_pk_mul_f32 v[34:35], v[34:35], v[38:39]
	v_cvt_pk_bf16_f32 v52, v56, v57
	v_cvt_pk_bf16_f32 v53, v58, v59
	v_cvt_pk_bf16_f32 v54, v48, v49
	v_cvt_pk_bf16_f32 v55, v50, v51
	v_cvt_pk_bf16_f32 v36, v40, v41
	v_cvt_pk_bf16_f32 v37, v42, v43
	v_cvt_pk_bf16_f32 v38, v32, v33
	v_cvt_pk_bf16_f32 v39, v34, v35
	global_store_dwordx4 v[186:187], v[52:55], off
	v_lshl_add_u64 v[186:187], v[186:187], 0, s[98:99]
	s_nop 0
	global_store_dwordx4 v[186:187], v[36:39], off
	v_lshl_add_u64 v[186:187], v[186:187], 0, s[98:99]
	v_mul_f32_e32 v178, 0xbfb8aa3b, v148
	v_mul_f32_e32 v179, v148, v148
	v_mul_f32_e32 v180, 0xbfb8aa3b, v149
	v_mul_f32_e32 v181, v149, v149
	v_pk_mul_f32 v[24:25], v[28:29], v[24:25]
	v_pk_mul_f32 v[8:9], v[12:13], v[8:9]
	v_pk_mul_f32 v[26:27], v[30:31], v[26:27]
	v_pk_mul_f32 v[10:11], v[14:15], v[10:11]
	v_pk_mul_f32 v[16:17], v[20:21], v[16:17]
	v_pk_mul_f32 v[0:1], v[4:5], v[0:1]
	v_pk_mul_f32 v[18:19], v[22:23], v[18:19]
	v_pk_mul_f32 v[2:3], v[6:7], v[2:3]
	v_rcp_f32_e32 v182, v179
	v_rcp_f32_e32 v184, v181
	v_pk_mul_f32 v[28:29], v[28:29], v[178:179] op_sel_hi:[1,0]
	v_pk_mul_f32 v[12:13], v[12:13], v[180:181] op_sel_hi:[1,0]
	v_pk_mul_f32 v[30:31], v[30:31], v[178:179] op_sel_hi:[1,0]
	v_pk_mul_f32 v[14:15], v[14:15], v[180:181] op_sel_hi:[1,0]
	v_pk_mul_f32 v[20:21], v[20:21], v[178:179] op_sel_hi:[1,0]
	v_pk_mul_f32 v[4:5], v[4:5], v[180:181] op_sel_hi:[1,0]
	v_pk_mul_f32 v[22:23], v[22:23], v[178:179] op_sel_hi:[1,0]
	v_pk_mul_f32 v[6:7], v[6:7], v[180:181] op_sel_hi:[1,0]
	v_exp_f32_e32 v28, v28
	v_exp_f32_e32 v29, v29
	v_exp_f32_e32 v12, v12
	v_exp_f32_e32 v13, v13
	v_exp_f32_e32 v30, v30
	v_exp_f32_e32 v31, v31
	v_exp_f32_e32 v14, v14
	v_exp_f32_e32 v15, v15
	v_exp_f32_e32 v20, v20
	v_exp_f32_e32 v21, v21
	v_exp_f32_e32 v4, v4
	v_exp_f32_e32 v5, v5
	v_exp_f32_e32 v22, v22
	v_exp_f32_e32 v23, v23
	v_exp_f32_e32 v6, v6
	v_exp_f32_e32 v7, v7
	v_pk_fma_f32 v[28:29], v[28:29], v[182:183], v[182:183] op_sel_hi:[1,0,0]
	v_pk_fma_f32 v[12:13], v[12:13], v[184:185], v[184:185] op_sel_hi:[1,0,0]
	v_pk_fma_f32 v[30:31], v[30:31], v[182:183], v[182:183] op_sel_hi:[1,0,0]
	v_pk_fma_f32 v[14:15], v[14:15], v[184:185], v[184:185] op_sel_hi:[1,0,0]
	v_pk_fma_f32 v[20:21], v[20:21], v[182:183], v[182:183] op_sel_hi:[1,0,0]
	v_pk_fma_f32 v[4:5], v[4:5], v[184:185], v[184:185] op_sel_hi:[1,0,0]
	v_pk_fma_f32 v[22:23], v[22:23], v[182:183], v[182:183] op_sel_hi:[1,0,0]
	v_pk_fma_f32 v[6:7], v[6:7], v[184:185], v[184:185] op_sel_hi:[1,0,0]
	v_rcp_f32_e32 v28, v28
	v_rcp_f32_e32 v29, v29
	v_rcp_f32_e32 v12, v12
	v_rcp_f32_e32 v13, v13
	v_rcp_f32_e32 v30, v30
	v_rcp_f32_e32 v31, v31
	v_rcp_f32_e32 v14, v14
	v_rcp_f32_e32 v15, v15
	v_rcp_f32_e32 v20, v20
	v_rcp_f32_e32 v21, v21
	v_rcp_f32_e32 v4, v4
	v_rcp_f32_e32 v5, v5
	v_rcp_f32_e32 v22, v22
	v_rcp_f32_e32 v23, v23
	v_rcp_f32_e32 v6, v6
	v_rcp_f32_e32 v7, v7
	v_pk_mul_f32 v[24:25], v[24:25], v[28:29]
	v_pk_mul_f32 v[8:9], v[8:9], v[12:13]
	v_pk_mul_f32 v[26:27], v[26:27], v[30:31]
	v_pk_mul_f32 v[10:11], v[10:11], v[14:15]
	v_pk_mul_f32 v[16:17], v[16:17], v[20:21]
	v_pk_mul_f32 v[0:1], v[0:1], v[4:5]
	v_pk_mul_f32 v[18:19], v[18:19], v[22:23]
	v_pk_mul_f32 v[2:3], v[2:3], v[6:7]
	v_cvt_pk_bf16_f32 v20, v24, v25
	v_cvt_pk_bf16_f32 v21, v26, v27
	v_cvt_pk_bf16_f32 v22, v16, v17
	v_cvt_pk_bf16_f32 v23, v18, v19
	v_cvt_pk_bf16_f32 v4, v8, v9
	v_cvt_pk_bf16_f32 v5, v10, v11
	v_cvt_pk_bf16_f32 v6, v0, v1
	v_cvt_pk_bf16_f32 v7, v2, v3
	global_store_dwordx4 v[186:187], v[20:23], off
	v_lshl_add_u64 v[186:187], v[186:187], 0, s[98:99]
	s_nop 0
	global_store_dwordx4 v[186:187], v[4:7], off
	s_andn2_b64 vcc, exec, s[4:5]
	s_mov_b64 s[4:5], -1
	s_cbranch_vccnz .LBB0_1144
	s_andn2_b64 vcc, exec, s[8:9]
	s_cbranch_vccnz .LBB0_1143
	s_barrier
	s_branch .LBB0_1143

.LBB0_2199:
	s_waitcnt lgkmcnt(0)
	s_mov_b32 s98, 0x16000
	s_mov_b32 s99, 0
	s_mov_b32 s100, 0x6e000
	s_mov_b32 s101, 0
	v_mov_b64_e32 v[188:189], s[64:65]
	v_lshl_or_b32 v190, s56, 7, v173
	v_mad_u64_u32 v[186:187], s[52:53], v160, s54, v[188:189]
	v_ashrrev_i32_e32 v191, 31, v190
	v_lshlrev_b64 v[190:191], 1, v[190:191]
	v_mul_f32_e32 v178, 0xbfb8aa3b, v166
	v_mul_f32_e32 v179, v166, v166
	v_mul_f32_e32 v180, 0xbfb8aa3b, v167
	v_mul_f32_e32 v181, v167, v167
	v_lshl_add_u64 v[186:187], v[186:187], 0, v[190:191]
	v_pk_mul_f32 v[120:121], v[124:125], v[120:121]
	v_pk_mul_f32 v[104:105], v[108:109], v[104:105]
	v_pk_mul_f32 v[122:123], v[126:127], v[122:123]
	v_pk_mul_f32 v[106:107], v[110:111], v[106:107]
	v_pk_mul_f32 v[112:113], v[116:117], v[112:113]
	v_pk_mul_f32 v[96:97], v[100:101], v[96:97]
	v_pk_mul_f32 v[114:115], v[118:119], v[114:115]
	v_pk_mul_f32 v[98:99], v[102:103], v[98:99]
	v_rcp_f32_e32 v182, v179
	v_rcp_f32_e32 v184, v181
	v_pk_mul_f32 v[124:125], v[124:125], v[178:179] op_sel_hi:[1,0]
	v_pk_mul_f32 v[108:109], v[108:109], v[180:181] op_sel_hi:[1,0]
	v_pk_mul_f32 v[126:127], v[126:127], v[178:179] op_sel_hi:[1,0]
	v_pk_mul_f32 v[110:111], v[110:111], v[180:181] op_sel_hi:[1,0]
	v_pk_mul_f32 v[116:117], v[116:117], v[178:179] op_sel_hi:[1,0]
	v_pk_mul_f32 v[100:101], v[100:101], v[180:181] op_sel_hi:[1,0]
	v_pk_mul_f32 v[118:119], v[118:119], v[178:179] op_sel_hi:[1,0]
	v_pk_mul_f32 v[102:103], v[102:103], v[180:181] op_sel_hi:[1,0]
	v_exp_f32_e32 v124, v124
	v_exp_f32_e32 v125, v125
	v_exp_f32_e32 v108, v108
	v_exp_f32_e32 v109, v109
	v_exp_f32_e32 v126, v126
	v_exp_f32_e32 v127, v127
	v_exp_f32_e32 v110, v110
	v_exp_f32_e32 v111, v111
	v_exp_f32_e32 v116, v116
	v_exp_f32_e32 v117, v117
	v_exp_f32_e32 v100, v100
	v_exp_f32_e32 v101, v101
	v_exp_f32_e32 v118, v118
	v_exp_f32_e32 v119, v119
	v_exp_f32_e32 v102, v102
	v_exp_f32_e32 v103, v103
	v_pk_fma_f32 v[124:125], v[124:125], v[182:183], v[182:183] op_sel_hi:[1,0,0]
	v_pk_fma_f32 v[108:109], v[108:109], v[184:185], v[184:185] op_sel_hi:[1,0,0]
	v_pk_fma_f32 v[126:127], v[126:127], v[182:183], v[182:183] op_sel_hi:[1,0,0]
	v_pk_fma_f32 v[110:111], v[110:111], v[184:185], v[184:185] op_sel_hi:[1,0,0]
	v_pk_fma_f32 v[116:117], v[116:117], v[182:183], v[182:183] op_sel_hi:[1,0,0]
	v_pk_fma_f32 v[100:101], v[100:101], v[184:185], v[184:185] op_sel_hi:[1,0,0]
	v_pk_fma_f32 v[118:119], v[118:119], v[182:183], v[182:183] op_sel_hi:[1,0,0]
	v_pk_fma_f32 v[102:103], v[102:103], v[184:185], v[184:185] op_sel_hi:[1,0,0]
	v_rcp_f32_e32 v124, v124
	v_rcp_f32_e32 v125, v125
	v_rcp_f32_e32 v108, v108
	v_rcp_f32_e32 v109, v109
	v_rcp_f32_e32 v126, v126
	v_rcp_f32_e32 v127, v127
	v_rcp_f32_e32 v110, v110
	v_rcp_f32_e32 v111, v111
	v_rcp_f32_e32 v116, v116
	v_rcp_f32_e32 v117, v117
	v_rcp_f32_e32 v100, v100
	v_rcp_f32_e32 v101, v101
	v_rcp_f32_e32 v118, v118
	v_rcp_f32_e32 v119, v119
	v_rcp_f32_e32 v102, v102
	v_rcp_f32_e32 v103, v103
	v_pk_mul_f32 v[120:121], v[120:121], v[124:125]
	v_pk_mul_f32 v[104:105], v[104:105], v[108:109]
	v_pk_mul_f32 v[122:123], v[122:123], v[126:127]
	v_pk_mul_f32 v[106:107], v[106:107], v[110:111]
	v_pk_mul_f32 v[112:113], v[112:113], v[116:117]
	v_pk_mul_f32 v[96:97], v[96:97], v[100:101]
	v_pk_mul_f32 v[114:115], v[114:115], v[118:119]
	v_pk_mul_f32 v[98:99], v[98:99], v[102:103]
	v_cvt_pk_bf16_f32 v116, v120, v121
	v_cvt_pk_bf16_f32 v117, v122, v123
	v_cvt_pk_bf16_f32 v118, v112, v113
	v_cvt_pk_bf16_f32 v119, v114, v115
	v_cvt_pk_bf16_f32 v100, v104, v105
	v_cvt_pk_bf16_f32 v101, v106, v107
	v_cvt_pk_bf16_f32 v102, v96, v97
	v_cvt_pk_bf16_f32 v103, v98, v99
	global_store_dwordx4 v[186:187], v[116:119], off
	v_lshl_add_u64 v[186:187], v[186:187], 0, s[98:99]
	s_nop 0
	global_store_dwordx4 v[186:187], v[100:103], off
	v_lshl_add_u64 v[186:187], v[186:187], 0, s[98:99]
	v_mul_f32_e32 v178, 0xbfb8aa3b, v162
	v_mul_f32_e32 v179, v162, v162
	v_mul_f32_e32 v180, 0xbfb8aa3b, v163
	v_mul_f32_e32 v181, v163, v163
	v_pk_mul_f32 v[88:89], v[92:93], v[88:89]
	v_pk_mul_f32 v[72:73], v[76:77], v[72:73]
	v_pk_mul_f32 v[90:91], v[94:95], v[90:91]
	v_pk_mul_f32 v[74:75], v[78:79], v[74:75]
	v_pk_mul_f32 v[80:81], v[84:85], v[80:81]
	v_pk_mul_f32 v[64:65], v[68:69], v[64:65]
	v_pk_mul_f32 v[82:83], v[86:87], v[82:83]
	v_pk_mul_f32 v[66:67], v[70:71], v[66:67]
	v_rcp_f32_e32 v182, v179
	v_rcp_f32_e32 v184, v181
	v_pk_mul_f32 v[92:93], v[92:93], v[178:179] op_sel_hi:[1,0]
	v_pk_mul_f32 v[76:77], v[76:77], v[180:181] op_sel_hi:[1,0]
	v_pk_mul_f32 v[94:95], v[94:95], v[178:179] op_sel_hi:[1,0]
	v_pk_mul_f32 v[78:79], v[78:79], v[180:181] op_sel_hi:[1,0]
	v_pk_mul_f32 v[84:85], v[84:85], v[178:179] op_sel_hi:[1,0]
	v_pk_mul_f32 v[68:69], v[68:69], v[180:181] op_sel_hi:[1,0]
	v_pk_mul_f32 v[86:87], v[86:87], v[178:179] op_sel_hi:[1,0]
	v_pk_mul_f32 v[70:71], v[70:71], v[180:181] op_sel_hi:[1,0]
	v_exp_f32_e32 v92, v92
	v_exp_f32_e32 v93, v93
	v_exp_f32_e32 v76, v76
	v_exp_f32_e32 v77, v77
	v_exp_f32_e32 v94, v94
	v_exp_f32_e32 v95, v95
	v_exp_f32_e32 v78, v78
	v_exp_f32_e32 v79, v79
	v_exp_f32_e32 v84, v84
	v_exp_f32_e32 v85, v85
	v_exp_f32_e32 v68, v68
	v_exp_f32_e32 v69, v69
	v_exp_f32_e32 v86, v86
	v_exp_f32_e32 v87, v87
	v_exp_f32_e32 v70, v70
	v_exp_f32_e32 v71, v71
	v_pk_fma_f32 v[92:93], v[92:93], v[182:183], v[182:183] op_sel_hi:[1,0,0]
	v_pk_fma_f32 v[76:77], v[76:77], v[184:185], v[184:185] op_sel_hi:[1,0,0]
	v_pk_fma_f32 v[94:95], v[94:95], v[182:183], v[182:183] op_sel_hi:[1,0,0]
	v_pk_fma_f32 v[78:79], v[78:79], v[184:185], v[184:185] op_sel_hi:[1,0,0]
	v_pk_fma_f32 v[84:85], v[84:85], v[182:183], v[182:183] op_sel_hi:[1,0,0]
	v_pk_fma_f32 v[68:69], v[68:69], v[184:185], v[184:185] op_sel_hi:[1,0,0]
	v_pk_fma_f32 v[86:87], v[86:87], v[182:183], v[182:183] op_sel_hi:[1,0,0]
	v_pk_fma_f32 v[70:71], v[70:71], v[184:185], v[184:185] op_sel_hi:[1,0,0]
	v_rcp_f32_e32 v92, v92
	v_rcp_f32_e32 v93, v93
	v_rcp_f32_e32 v76, v76
	v_rcp_f32_e32 v77, v77
	v_rcp_f32_e32 v94, v94
	v_rcp_f32_e32 v95, v95
	v_rcp_f32_e32 v78, v78
	v_rcp_f32_e32 v79, v79
	v_rcp_f32_e32 v84, v84
	v_rcp_f32_e32 v85, v85
	v_rcp_f32_e32 v68, v68
	v_rcp_f32_e32 v69, v69
	v_rcp_f32_e32 v86, v86
	v_rcp_f32_e32 v87, v87
	v_rcp_f32_e32 v70, v70
	v_rcp_f32_e32 v71, v71
	v_pk_mul_f32 v[88:89], v[88:89], v[92:93]
	v_pk_mul_f32 v[72:73], v[72:73], v[76:77]
	v_pk_mul_f32 v[90:91], v[90:91], v[94:95]
	v_pk_mul_f32 v[74:75], v[74:75], v[78:79]
	v_pk_mul_f32 v[80:81], v[80:81], v[84:85]
	v_pk_mul_f32 v[64:65], v[64:65], v[68:69]
	v_pk_mul_f32 v[82:83], v[82:83], v[86:87]
	v_pk_mul_f32 v[66:67], v[66:67], v[70:71]
	v_cvt_pk_bf16_f32 v84, v88, v89
	v_cvt_pk_bf16_f32 v85, v90, v91
	v_cvt_pk_bf16_f32 v86, v80, v81
	v_cvt_pk_bf16_f32 v87, v82, v83
	v_cvt_pk_bf16_f32 v68, v72, v73
	v_cvt_pk_bf16_f32 v69, v74, v75
	v_cvt_pk_bf16_f32 v70, v64, v65
	v_cvt_pk_bf16_f32 v71, v66, v67
	global_store_dwordx4 v[186:187], v[84:87], off
	v_lshl_add_u64 v[186:187], v[186:187], 0, s[98:99]
	s_nop 0
	global_store_dwordx4 v[186:187], v[68:71], off
	v_lshl_add_u64 v[186:187], v[186:187], 0, s[100:101]
	v_mul_f32_e32 v178, 0xbfb8aa3b, v154
	v_mul_f32_e32 v179, v154, v154
	v_mul_f32_e32 v180, 0xbfb8aa3b, v155
	v_mul_f32_e32 v181, v155, v155
	v_pk_mul_f32 v[56:57], v[60:61], v[56:57]
	v_pk_mul_f32 v[40:41], v[44:45], v[40:41]
	v_pk_mul_f32 v[58:59], v[62:63], v[58:59]
	v_pk_mul_f32 v[42:43], v[46:47], v[42:43]
	v_pk_mul_f32 v[48:49], v[52:53], v[48:49]
	v_pk_mul_f32 v[32:33], v[36:37], v[32:33]
	v_pk_mul_f32 v[50:51], v[54:55], v[50:51]
	v_pk_mul_f32 v[34:35], v[38:39], v[34:35]
	v_rcp_f32_e32 v182, v179
	v_rcp_f32_e32 v184, v181
	v_pk_mul_f32 v[60:61], v[60:61], v[178:179] op_sel_hi:[1,0]
	v_pk_mul_f32 v[44:45], v[44:45], v[180:181] op_sel_hi:[1,0]
	v_pk_mul_f32 v[62:63], v[62:63], v[178:179] op_sel_hi:[1,0]
	v_pk_mul_f32 v[46:47], v[46:47], v[180:181] op_sel_hi:[1,0]
	v_pk_mul_f32 v[52:53], v[52:53], v[178:179] op_sel_hi:[1,0]
	v_pk_mul_f32 v[36:37], v[36:37], v[180:181] op_sel_hi:[1,0]
	v_pk_mul_f32 v[54:55], v[54:55], v[178:179] op_sel_hi:[1,0]
	v_pk_mul_f32 v[38:39], v[38:39], v[180:181] op_sel_hi:[1,0]
	v_exp_f32_e32 v60, v60
	v_exp_f32_e32 v61, v61
	v_exp_f32_e32 v44, v44
	v_exp_f32_e32 v45, v45
	v_exp_f32_e32 v62, v62
	v_exp_f32_e32 v63, v63
	v_exp_f32_e32 v46, v46
	v_exp_f32_e32 v47, v47
	v_exp_f32_e32 v52, v52
	v_exp_f32_e32 v53, v53
	v_exp_f32_e32 v36, v36
	v_exp_f32_e32 v37, v37
	v_exp_f32_e32 v54, v54
	v_exp_f32_e32 v55, v55
	v_exp_f32_e32 v38, v38
	v_exp_f32_e32 v39, v39
	v_pk_fma_f32 v[60:61], v[60:61], v[182:183], v[182:183] op_sel_hi:[1,0,0]
	v_pk_fma_f32 v[44:45], v[44:45], v[184:185], v[184:185] op_sel_hi:[1,0,0]
	v_pk_fma_f32 v[62:63], v[62:63], v[182:183], v[182:183] op_sel_hi:[1,0,0]
	v_pk_fma_f32 v[46:47], v[46:47], v[184:185], v[184:185] op_sel_hi:[1,0,0]
	v_pk_fma_f32 v[52:53], v[52:53], v[182:183], v[182:183] op_sel_hi:[1,0,0]
	v_pk_fma_f32 v[36:37], v[36:37], v[184:185], v[184:185] op_sel_hi:[1,0,0]
	v_pk_fma_f32 v[54:55], v[54:55], v[182:183], v[182:183] op_sel_hi:[1,0,0]
	v_pk_fma_f32 v[38:39], v[38:39], v[184:185], v[184:185] op_sel_hi:[1,0,0]
	v_rcp_f32_e32 v60, v60
	v_rcp_f32_e32 v61, v61
	v_rcp_f32_e32 v44, v44
	v_rcp_f32_e32 v45, v45
	v_rcp_f32_e32 v62, v62
	v_rcp_f32_e32 v63, v63
	v_rcp_f32_e32 v46, v46
	v_rcp_f32_e32 v47, v47
	v_rcp_f32_e32 v52, v52
	v_rcp_f32_e32 v53, v53
	v_rcp_f32_e32 v36, v36
	v_rcp_f32_e32 v37, v37
	v_rcp_f32_e32 v54, v54
	v_rcp_f32_e32 v55, v55
	v_rcp_f32_e32 v38, v38
	v_rcp_f32_e32 v39, v39
	v_pk_mul_f32 v[56:57], v[56:57], v[60:61]
	v_pk_mul_f32 v[40:41], v[40:41], v[44:45]
	v_pk_mul_f32 v[58:59], v[58:59], v[62:63]
	v_pk_mul_f32 v[42:43], v[42:43], v[46:47]
	v_pk_mul_f32 v[48:49], v[48:49], v[52:53]
	v_pk_mul_f32 v[32:33], v[32:33], v[36:37]
	v_pk_mul_f32 v[50:51], v[50:51], v[54:55]
	v_pk_mul_f32 v[34:35], v[34:35], v[38:39]
	v_cvt_pk_bf16_f32 v52, v56, v57
	v_cvt_pk_bf16_f32 v53, v58, v59
	v_cvt_pk_bf16_f32 v54, v48, v49
	v_cvt_pk_bf16_f32 v55, v50, v51
	v_cvt_pk_bf16_f32 v36, v40, v41
	v_cvt_pk_bf16_f32 v37, v42, v43
	v_cvt_pk_bf16_f32 v38, v32, v33
	v_cvt_pk_bf16_f32 v39, v34, v35
	global_store_dwordx4 v[186:187], v[52:55], off
	v_lshl_add_u64 v[186:187], v[186:187], 0, s[98:99]
	s_nop 0
	global_store_dwordx4 v[186:187], v[36:39], off
	v_lshl_add_u64 v[186:187], v[186:187], 0, s[98:99]
	v_mul_f32_e32 v178, 0xbfb8aa3b, v148
	v_mul_f32_e32 v179, v148, v148
	v_mul_f32_e32 v180, 0xbfb8aa3b, v149
	v_mul_f32_e32 v181, v149, v149
	v_pk_mul_f32 v[24:25], v[28:29], v[24:25]
	v_pk_mul_f32 v[8:9], v[12:13], v[8:9]
	v_pk_mul_f32 v[26:27], v[30:31], v[26:27]
	v_pk_mul_f32 v[10:11], v[14:15], v[10:11]
	v_pk_mul_f32 v[16:17], v[20:21], v[16:17]
	v_pk_mul_f32 v[0:1], v[4:5], v[0:1]
	v_pk_mul_f32 v[18:19], v[22:23], v[18:19]
	v_pk_mul_f32 v[2:3], v[6:7], v[2:3]
	v_rcp_f32_e32 v182, v179
	v_rcp_f32_e32 v184, v181
	v_pk_mul_f32 v[28:29], v[28:29], v[178:179] op_sel_hi:[1,0]
	v_pk_mul_f32 v[12:13], v[12:13], v[180:181] op_sel_hi:[1,0]
	v_pk_mul_f32 v[30:31], v[30:31], v[178:179] op_sel_hi:[1,0]
	v_pk_mul_f32 v[14:15], v[14:15], v[180:181] op_sel_hi:[1,0]
	v_pk_mul_f32 v[20:21], v[20:21], v[178:179] op_sel_hi:[1,0]
	v_pk_mul_f32 v[4:5], v[4:5], v[180:181] op_sel_hi:[1,0]
	v_pk_mul_f32 v[22:23], v[22:23], v[178:179] op_sel_hi:[1,0]
	v_pk_mul_f32 v[6:7], v[6:7], v[180:181] op_sel_hi:[1,0]
	v_exp_f32_e32 v28, v28
	v_exp_f32_e32 v29, v29
	v_exp_f32_e32 v12, v12
	v_exp_f32_e32 v13, v13
	v_exp_f32_e32 v30, v30
	v_exp_f32_e32 v31, v31
	v_exp_f32_e32 v14, v14
	v_exp_f32_e32 v15, v15
	v_exp_f32_e32 v20, v20
	v_exp_f32_e32 v21, v21
	v_exp_f32_e32 v4, v4
	v_exp_f32_e32 v5, v5
	v_exp_f32_e32 v22, v22
	v_exp_f32_e32 v23, v23
	v_exp_f32_e32 v6, v6
	v_exp_f32_e32 v7, v7
	v_pk_fma_f32 v[28:29], v[28:29], v[182:183], v[182:183] op_sel_hi:[1,0,0]
	v_pk_fma_f32 v[12:13], v[12:13], v[184:185], v[184:185] op_sel_hi:[1,0,0]
	v_pk_fma_f32 v[30:31], v[30:31], v[182:183], v[182:183] op_sel_hi:[1,0,0]
	v_pk_fma_f32 v[14:15], v[14:15], v[184:185], v[184:185] op_sel_hi:[1,0,0]
	v_pk_fma_f32 v[20:21], v[20:21], v[182:183], v[182:183] op_sel_hi:[1,0,0]
	v_pk_fma_f32 v[4:5], v[4:5], v[184:185], v[184:185] op_sel_hi:[1,0,0]
	v_pk_fma_f32 v[22:23], v[22:23], v[182:183], v[182:183] op_sel_hi:[1,0,0]
	v_pk_fma_f32 v[6:7], v[6:7], v[184:185], v[184:185] op_sel_hi:[1,0,0]
	v_rcp_f32_e32 v28, v28
	v_rcp_f32_e32 v29, v29
	v_rcp_f32_e32 v12, v12
	v_rcp_f32_e32 v13, v13
	v_rcp_f32_e32 v30, v30
	v_rcp_f32_e32 v31, v31
	v_rcp_f32_e32 v14, v14
	v_rcp_f32_e32 v15, v15
	v_rcp_f32_e32 v20, v20
	v_rcp_f32_e32 v21, v21
	v_rcp_f32_e32 v4, v4
	v_rcp_f32_e32 v5, v5
	v_rcp_f32_e32 v22, v22
	v_rcp_f32_e32 v23, v23
	v_rcp_f32_e32 v6, v6
	v_rcp_f32_e32 v7, v7
	v_pk_mul_f32 v[24:25], v[24:25], v[28:29]
	v_pk_mul_f32 v[8:9], v[8:9], v[12:13]
	v_pk_mul_f32 v[26:27], v[26:27], v[30:31]
	v_pk_mul_f32 v[10:11], v[10:11], v[14:15]
	v_pk_mul_f32 v[16:17], v[16:17], v[20:21]
	v_pk_mul_f32 v[0:1], v[0:1], v[4:5]
	v_pk_mul_f32 v[18:19], v[18:19], v[22:23]
	v_pk_mul_f32 v[2:3], v[2:3], v[6:7]
	v_cvt_pk_bf16_f32 v20, v24, v25
	v_cvt_pk_bf16_f32 v21, v26, v27
	v_cvt_pk_bf16_f32 v22, v16, v17
	v_cvt_pk_bf16_f32 v23, v18, v19
	v_cvt_pk_bf16_f32 v4, v8, v9
	v_cvt_pk_bf16_f32 v5, v10, v11
	v_cvt_pk_bf16_f32 v6, v0, v1
	v_cvt_pk_bf16_f32 v7, v2, v3
	global_store_dwordx4 v[186:187], v[20:23], off
	v_lshl_add_u64 v[186:187], v[186:187], 0, s[98:99]
	s_nop 0
	global_store_dwordx4 v[186:187], v[4:7], off
	s_andn2_b64 vcc, exec, s[4:5]
	s_mov_b64 s[4:5], -1
	s_cbranch_vccnz .LBB0_2188
	s_andn2_b64 vcc, exec, s[8:9]
	s_cbranch_vccnz .LBB0_2187
	s_barrier
	s_branch .LBB0_2187
